# RG-LRU scan: x / gate loads use SGPR base + 32-bit lane offset (drops 54 of the 64-bit VALU address adds in the five step copies)
# baseline (speedup 1.0000x reference)
; #define LAS __attribute__((address_space(3)))
; DI unsigned pk2(float lo, float hi) { f32x2 v = {lo, hi}; bf16v2 b = __builtin_convertvector(v, bf16v2); return __builtin_bit_cast(unsigned, b); }
; DI void rglru_scan_unit(Frame& F, const Mix0Args& a, int u) {
;     ...
;     f32x4 cq0[4], cq1[4], cq2[4], cq3[4];
; #pragma unroll
;     for (int i = 0; i < 4; ++i) cq0[i] = cq1[i] = cq2[i] = cq3[i] = (f32x4){0.f, 0.f, 0.f, 0.f};
;     { const int j = tid & 31, kg = tid >> 5; float wv[8], xv[8];
; #pragma unroll
;       for (int i = 0; i < 8; ++i) { const size_t o = ((size_t)(nb * 128 + 8 * kg + i)) * 128 + qq * 32 + j; wv[i] = a.wa[o]; xv[i] = a.wx[o]; }
;       u32x4 p; p.x = pk2(wv[0], wv[1]); p.y = pk2(wv[2], wv[3]); p.z = pk2(wv[4], wv[5]); p.w = pk2(wv[6], wv[7]); *(LAS u32x4*)(WAT + j * S128 + kg * 16) = p;
;       p.x = pk2(xv[0], xv[1]); p.y = pk2(xv[2], xv[3]); p.z = pk2(xv[4], xv[5]); p.w = pk2(xv[6], xv[7]); *(LAS u32x4*)(WXT + j * S128 + kg * 16) = p; }
;     if (tid < 64) HPREV[(tid & 31) * 20 + (tid >> 5)] = 0.f;
;     const int c2 = tid & 63, rg = tid >> 6;
;     float cw[4][2], cbs[2];
; #pragma unroll
;     for (int j = 0; j < 2; ++j) { const int ch = cb + 2 * c2 + j; cbs[j] = a.conv_b[ch];
; #pragma unroll
;         for (int k = 0; k < 4; ++k) cw[k][j] = a.conv_w[k * 4096 + ch]; }
;     const int ltile = w & 3, jtile = w >> 2, l0_ = 16 * ltile, jj = 16 * jtile + fr, co = cb + qq * 32 + jj;
;     const float bav = a.ba[co], bxv = a.bx[co], sp8l2 = 8.0f * LOG2E * log1pf(__expf(-a.lam[co]));
;     const size_t rowbase = (size_t)b * SEQ;
;     const bf16* xcol = a.proj + C_XB + cb + 2 * c2;
;     const bf16* gbcol = a.proj + C_GB + co; bf16* obcol = a.outp + a.ob_col + co;
;     unsigned xr[11], gbr[4];
.LBB0_246:
	v_mul_f32_e32 v6, 0xbfb8aa3b, v8
	v_exp_f32_e32 v8, v6
	s_mov_b32 s8, 0x3f2aaaab
	s_mov_b32 s41, s97
	s_waitcnt vmcnt(3)
	v_and_b32_e32 v181, 0xffff, v2
	v_add_f32_e32 v9, 1.0, v8
	v_frexp_mant_f32_e32 v11, v9
	v_cvt_f64_f32_e32 v[6:7], v9
	v_add_f32_e32 v10, -1.0, v9
	v_frexp_exp_i32_f64_e32 v6, v[6:7]
	v_cmp_gt_f32_e32 vcc, s8, v11
	v_sub_f32_e32 v12, v10, v9
	v_sub_f32_e32 v10, v8, v10
	v_subbrev_co_u32_e32 v6, vcc, 0, v6, vcc
	v_add_f32_e32 v12, 1.0, v12
	v_sub_u32_e32 v7, 0, v6
	v_add_f32_e32 v10, v10, v12
	v_ldexp_f32 v9, v9, v7
	v_ldexp_f32 v7, v10, v7
	v_add_f32_e32 v10, -1.0, v9
	v_add_f32_e32 v13, 1.0, v9
	v_add_f32_e32 v11, 1.0, v10
	v_add_f32_e32 v14, -1.0, v13
	v_sub_f32_e32 v11, v9, v11
	v_sub_f32_e32 v9, v9, v14
	v_add_f32_e32 v11, v7, v11
	v_add_f32_e32 v7, v7, v9
	v_add_f32_e32 v9, v13, v7
	v_rcp_f32_e32 v14, v9
	v_add_f32_e32 v12, v10, v11
	v_sub_f32_e32 v10, v12, v10
	v_sub_f32_e32 v10, v11, v10
	v_sub_f32_e32 v11, v9, v13
	v_sub_f32_e32 v7, v7, v11
	v_mul_f32_e32 v11, v12, v14
	v_mul_f32_e32 v13, v9, v11
	v_fma_f32 v15, v11, v9, -v13
	v_fmac_f32_e32 v15, v11, v7
	v_add_f32_e32 v16, v13, v15
	v_sub_f32_e32 v17, v12, v16
	v_sub_f32_e32 v12, v12, v17
	v_sub_f32_e32 v13, v16, v13
	v_sub_f32_e32 v12, v12, v16
	v_add_f32_e32 v10, v10, v12
	v_sub_f32_e32 v12, v13, v15
	v_add_f32_e32 v10, v12, v10
	v_add_f32_e32 v12, v17, v10
	v_mul_f32_e32 v13, v14, v12
	v_mul_f32_e32 v15, v9, v13
	v_fma_f32 v9, v13, v9, -v15
	v_fmac_f32_e32 v9, v13, v7
	v_sub_f32_e32 v7, v17, v12
	v_add_f32_e32 v7, v10, v7
	v_add_f32_e32 v10, v15, v9
	v_sub_f32_e32 v16, v12, v10
	v_sub_f32_e32 v12, v12, v16
	v_sub_f32_e32 v15, v10, v15
	v_sub_f32_e32 v10, v12, v10
	v_add_f32_e32 v7, v7, v10
	v_sub_f32_e32 v9, v15, v9
	v_cvt_f32_i32_e32 v6, v6
	v_add_f32_e32 v7, v9, v7
	v_add_f32_e32 v9, v11, v13
	v_add_f32_e32 v7, v16, v7
	v_sub_f32_e32 v10, v9, v11
	v_mul_f32_e32 v7, v14, v7
	v_sub_f32_e32 v10, v13, v10
	v_add_f32_e32 v7, v10, v7
	v_mul_f32_e32 v13, 0x3f317218, v6
	s_mov_b32 s8, 0x3f317218
	v_add_f32_e32 v10, v9, v7
	v_fma_f32 v14, v6, s8, -v13
	v_mul_f32_e32 v11, v10, v10
	v_fmac_f32_e32 v14, 0xb102e308, v6
	v_sub_f32_e32 v6, v10, v9
	v_fmamk_f32 v12, v11, 0x3e9b6dac, v157
	v_sub_f32_e32 v6, v7, v6
	v_add_f32_e32 v7, v13, v14
	v_fmaak_f32 v12, v11, v12, 0x3f2aaada
	v_sub_f32_e32 v9, v7, v13
	v_ldexp_f32 v13, v10, 1
	v_mul_f32_e32 v10, v10, v11
	v_mul_f32_e32 v10, v10, v12
	v_add_f32_e32 v11, v13, v10
	v_sub_f32_e32 v12, v11, v13
	v_ldexp_f32 v6, v6, 1
	v_sub_f32_e32 v10, v10, v12
	v_add_f32_e32 v6, v6, v10
	v_add_f32_e32 v10, v11, v6
	v_sub_f32_e32 v11, v10, v11
	v_sub_f32_e32 v6, v6, v11
	v_add_f32_e32 v11, v7, v10
	v_sub_f32_e32 v12, v11, v7
	v_sub_f32_e32 v13, v11, v12
	v_sub_f32_e32 v9, v14, v9
	v_sub_f32_e32 v7, v7, v13
	v_sub_f32_e32 v10, v10, v12
	v_add_f32_e32 v7, v10, v7
	v_add_f32_e32 v10, v9, v6
	v_sub_f32_e32 v12, v10, v9
	v_sub_f32_e32 v13, v10, v12
	v_sub_f32_e32 v9, v9, v13
	v_sub_f32_e32 v6, v6, v12
	v_add_f32_e32 v7, v10, v7
	v_add_f32_e32 v6, v6, v9
	v_add_f32_e32 v9, v11, v7
	v_sub_f32_e32 v10, v9, v11
	v_sub_f32_e32 v7, v7, v10
	v_add_f32_e32 v6, v6, v7
	s_mov_b32 s8, 0x7f800000
	v_add_f32_e32 v6, v9, v6
	v_cmp_neq_f32_e32 vcc, s8, v8
	s_mov_b32 s8, 0x33800000
	s_waitcnt vmcnt(2)
	v_and_b32_e32 v180, 0xffff, v3
	v_cndmask_b32_e32 v6, v160, v6, vcc
	v_cmp_ngt_f32_e32 vcc, -1.0, v8
	s_waitcnt vmcnt(1)
	v_and_b32_e32 v179, 0xffff, v4
	s_waitcnt vmcnt(0)
	v_and_b32_e32 v178, 0xffff, v5
	v_cndmask_b32_e32 v6, v161, v6, vcc
	v_cmp_neq_f32_e32 vcc, -1.0, v8
	v_mov_b32_e32 v115, v83
	s_mul_hi_i32 s81, s2, 0x18000000
	v_cndmask_b32_e32 v6, v162, v6, vcc
	v_cmp_lt_f32_e64 vcc, |v8|, s8
	s_and_b32 s8, s43, 0xfe0
	v_add_lshl_u32 v114, v153, s8, 1
	s_lshl_b32 s8, s43, 1
	s_and_b32 s40, s8, 0x1f00
	s_cmp_lg_u32 s3, 0
	s_cselect_b64 s[8:9], -1, 0
	v_writelane_b32 v252, s8, 6
	v_cndmask_b32_e32 v6, v6, v8, vcc
	v_mul_f32_e32 v168, 0x4138aa3b, v6
	v_writelane_b32 v252, s9, 7
	s_cmp_eq_u32 s3, 0
	s_mul_i32 s80, s2, 0x18000000
	v_writelane_b32 v252, s40, 8
	s_nop 1
	v_writelane_b32 v252, s41, 9
	s_cbranch_scc1 .LBB0_304
	v_readlane_b32 s8, v253, 50
	s_lshl_b32 s36, s8, 6
	v_mad_i64_i32 v[2:3], s[8:9], s2, v163, v[114:115]
	s_or_b64 s[8:9], s[80:81], s[40:41]
	v_mov_b32_e32 v54, 0
	s_lshl_b32 s76, s3, 2
	v_lshl_add_u64 v[116:117], v[94:95], 0, v[2:3]
	v_lshl_add_u64 v[118:119], v[96:97], 0, v[2:3]
	v_lshl_add_u64 v[120:121], v[98:99], 0, s[8:9]
	s_nop 0
	v_readfirstlane_b32 s98, v120
	v_readfirstlane_b32 s99, v118
	s_nop 1
	v_subrev_u32_e32 v208, s98, v120
	v_subrev_u32_e32 v209, s99, v118
	s_mov_b32 s77, 0
	s_mov_b64 s[8:9], 0
	v_add_u32_e32 v113, s36, v146
	v_add_u32_e32 v177, s36, v151
	v_readlane_b32 s86, v253, 63
	v_mov_b32_e32 v55, v54
	v_mov_b32_e32 v56, v54
	v_mov_b32_e32 v57, v54
	v_mov_b32_e32 v58, v54
	v_mov_b32_e32 v59, v54
	v_mov_b32_e32 v60, v54
	v_mov_b32_e32 v61, v54
	v_mov_b32_e32 v62, v54
	v_mov_b32_e32 v63, v54
	v_mov_b32_e32 v64, v54
	v_mov_b32_e32 v65, v54
	v_mov_b32_e32 v50, v54
	v_mov_b32_e32 v51, v54
	v_mov_b32_e32 v52, v54
	v_mov_b32_e32 v53, v54
	v_mov_b32_e32 v34, v54
	v_mov_b32_e32 v35, v54
	v_mov_b32_e32 v36, v54
	v_mov_b32_e32 v37, v54
	v_mov_b32_e32 v38, v54
	v_mov_b32_e32 v39, v54
	v_mov_b32_e32 v40, v54
	v_mov_b32_e32 v41, v54
	v_mov_b32_e32 v42, v54
	v_mov_b32_e32 v43, v54
	v_mov_b32_e32 v44, v54
	v_mov_b32_e32 v45, v54
	v_mov_b32_e32 v46, v54
	v_mov_b32_e32 v47, v54
	v_mov_b32_e32 v48, v54
	v_mov_b32_e32 v49, v54
	v_mov_b32_e32 v18, v54
	v_mov_b32_e32 v19, v54
	v_mov_b32_e32 v20, v54
	v_mov_b32_e32 v21, v54
	v_mov_b32_e32 v22, v54
	v_mov_b32_e32 v23, v54
	v_mov_b32_e32 v24, v54
	v_mov_b32_e32 v25, v54
	v_mov_b32_e32 v26, v54
	v_mov_b32_e32 v27, v54
	v_mov_b32_e32 v28, v54
	v_mov_b32_e32 v29, v54
	v_mov_b32_e32 v30, v54
	v_mov_b32_e32 v31, v54
	v_mov_b32_e32 v32, v54
	v_mov_b32_e32 v33, v54
	v_mov_b32_e32 v2, v54
	v_mov_b32_e32 v3, v54
	v_mov_b32_e32 v4, v54
	v_mov_b32_e32 v5, v54
	v_mov_b32_e32 v6, v54
	v_mov_b32_e32 v7, v54
	v_mov_b32_e32 v8, v54
	v_mov_b32_e32 v9, v54
	v_mov_b32_e32 v10, v54
	v_mov_b32_e32 v11, v54
	v_mov_b32_e32 v12, v54
	v_mov_b32_e32 v13, v54
	v_mov_b32_e32 v14, v54
	v_mov_b32_e32 v15, v54
	v_mov_b32_e32 v16, v54
	v_mov_b32_e32 v17, v54
	s_branch .LBB0_249

.LBB0_263:
	s_waitcnt vmcnt(4)
	v_lshl_add_u64 v[50:51], v[120:121], 0, s[8:9]
	s_nop 0
	s_nop 0
	v_lshl_add_u64 v[52:53], v[118:119], 0, s[8:9]
	s_nop 0
	v_readfirstlane_b32 s98, v50
	v_readfirstlane_b32 s99, v51
	s_add_u32 s100, s98, 0x258e4000
	s_addc_u32 s101, s99, 0x0
	global_load_dword v18, v208, s[100:101]
	s_nop 0
	s_nop 0
	s_mul_i32 s36, s36, s94
	s_add_u32 s100, s98, 0x258f0000
	s_addc_u32 s101, s99, 0x0
	global_load_dword v19, v208, s[100:101]
	s_nop 0
	s_nop 0
	s_add_i32 s36, s36, s95
	s_add_u32 s100, s98, 0x258fc000
	s_addc_u32 s101, s99, 0x0
	global_load_dword v20, v208, s[100:101]
	s_nop 0
	s_nop 0
	s_add_i32 s37, s36, 0xffff7780
	s_add_u32 s100, s98, 0x25908000
	s_addc_u32 s101, s99, 0x0
	global_load_dword v21, v208, s[100:101]
	s_mov_b64 s[100:101], 0x25914000
	v_lshl_add_u64 v[2:3], v[50:51], 0, s[100:101]
	s_cmp_lt_i32 s36, 0x8880
	global_load_dword v22, v[2:3], off
	s_nop 0
	s_nop 0
	s_cselect_b32 s87, s36, s37
	s_add_u32 s100, s98, 0x25920000
	s_addc_u32 s101, s99, 0x0
	global_load_dword v23, v208, s[100:101]
	s_mov_b64 s[100:101], 0x2592c000
	v_lshl_add_u64 v[2:3], v[50:51], 0, s[100:101]
	s_cmpk_gt_i32 s87, 0x1fff
	global_load_dword v24, v[2:3], off
	s_nop 0
	s_nop 0
	s_cselect_b64 s[40:41], -1, 0
	s_add_u32 s100, s98, 0x25938000
	s_addc_u32 s101, s99, 0x0
	global_load_dword v27, v208, s[100:101]
	s_mov_b64 s[100:101], 0x25944000
	v_lshl_add_u64 v[2:3], v[50:51], 0, s[100:101]
	s_cmpk_lt_i32 s87, 0x2000
	global_load_dword v25, v[2:3], off
	s_mov_b64 s[100:101], 0x25950000
	v_lshl_add_u64 v[2:3], v[50:51], 0, s[100:101]
	global_load_dword v26, v[2:3], off
	s_mov_b64 s[100:101], 0x2595c000
	v_lshl_add_u64 v[2:3], v[50:51], 0, s[100:101]
	global_load_dword v28, v[2:3], off
	s_mov_b64 s[100:101], 0x2560a000
	v_lshl_add_u64 v[2:3], v[52:53], 0, s[100:101]
	global_load_ushort v37, v[2:3], off
	s_mov_b64 s[100:101], 0x25616000
	v_lshl_add_u64 v[2:3], v[52:53], 0, s[100:101]
	global_load_ushort v36, v[2:3], off
	s_mov_b64 s[100:101], 0x25622000
	v_lshl_add_u64 v[2:3], v[52:53], 0, s[100:101]
	global_load_ushort v34, v[2:3], off
	s_mov_b64 s[100:101], 0x2562e000
	v_lshl_add_u64 v[2:3], v[52:53], 0, s[100:101]
	global_load_ushort v35, v[2:3], off
	s_cbranch_scc1 .LBB0_266
	s_cmpk_gt_u32 s87, 0x687f
	s_cbranch_scc0 .LBB0_267
	s_add_i32 s84, s87, 0xffff9780
	s_mov_b64 s[36:37], s[52:53]
	s_movk_i32 s78, 0x1000
	s_cbranch_execz .LBB0_268
	s_branch .LBB0_269

; #define LAS __attribute__((address_space(3)))
; DI float bf2f(unsigned h) { return __uint_as_float(h << 16); }
; DI float fexp2(float x) { return __builtin_amdgcn_exp2f(x); }
; DI float fsigmoid(float x) { return frcp(1.0f + fexp2(-LOG2E * x)); }
; DI void cv_issue_q(const CvJob& j, int idx, int lane, f32x4 (&v)[4], int r0) {
;     const float* W; int K, N, item; bf16* WT; const float* ks; cv_decode(j, idx, W, K, N, WT, ks, item);
;     const int nblk = N / 64, kb = item / nblk, nb = item % nblk, k0 = 64 * kb, n0 = 64 * nb, q = lane >> 4, c16 = lane & 15;
;     const char* ub = (const char*)(W + (size_t)(k0 + r0) * N + n0);
;     const unsigned vo = (unsigned)((16 * q) * N + 4 * c16) * 4u;
; #pragma unroll
;     for (int i = 0; i < 4; ++i) v[i] = *(const f32x4*)(ub + (size_t)i * N * 4 + vo);
; }
; DI void rglru_scan_unit(Frame& F, const Mix0Args& a, int u) {
;     ...
;         { bf16x8 xf[4], waf[4], wxf[4]; unsigned xcr[4];
; #pragma unroll
;           for (int ks = 0; ks < 4; ++ks) { xf[ks] = *(const LAS bf16x8*)(XCc + (l0_ + fr) * S128 + ks * 64 + fq * 16);
;               waf[ks] = *(const LAS bf16x8*)(WAT + (16 * jtile + fr) * S128 + ks * 64 + fq * 16); wxf[ks] = *(const LAS bf16x8*)(WXT + (16 * jtile + fr) * S128 + ks * 64 + fq * 16); }
; #pragma unroll
;           for (int r = 0; r < 4; ++r) xcr[r] = *(const LAS unsigned short*)(XCc + (l0_ + 4 * fq + r) * S128 + (qq * 32 + jj) * 2);
;           f32x4 R = zero4, I = zero4;
; #pragma unroll
;           for (int ks = 0; ks < 4; ++ks) { R = __builtin_amdgcn_mfma_f32_16x16x32_bf16(xf[ks], waf[ks], R, 0, 0, 0); I = __builtin_amdgcn_mfma_f32_16x16x32_bf16(xf[ks], wxf[ks], I, 0, 0, 0); }
; #pragma unroll
;           for (int r = 0; r < 4; ++r) {
;               const float rr = fsigmoid(R[r] + bav), ig = fsigmoid(I[r] + bxv);
;               const float aa = fexp2(-sp8l2 * rr); const float om = __builtin_fmaf(-aa, aa, 1.0f);
;               av[r] = aa; uv[r] = __builtin_sqrtf(om) * (ig * bf2f(xcr[r]));
;               Hseg = aa * Hseg + uv[r]; Aseg *= aa; } }
;         const int sgi = ltile * 4 + fq;
;         SEGA[jj * 20 + sgi] = Aseg; SEGH[jj * 20 + sgi] = Hseg;
.LBB0_269:
	s_lshr_b32 s79, s78, 6
	v_cvt_f32_u32_e32 v2, s79
	s_sub_i32 s90, 0, s79
	s_abs_i32 s89, s84
	s_ashr_i32 s88, s84, 31
	v_rcp_iflag_f32_e32 v2, v2
	v_mul_u32_u24_e32 v29, s78, v102
	v_or_b32_e32 v29, v29, v125
	v_lshlrev_b32_e32 v82, 2, v29
	v_mul_f32_e32 v2, 0x4f7ffffe, v2
	v_cvt_u32_f32_e32 v2, v2
	ds_read_b128 v[6:9], v103 offset:36864
	v_readfirstlane_b32 s91, v2
	s_mul_i32 s90, s90, s91
	s_mul_hi_u32 s90, s91, s90
	s_add_i32 s91, s91, s90
	s_mul_hi_u32 s90, s89, s91
	s_mul_i32 s91, s90, s79
	s_sub_i32 s89, s89, s91
	s_add_i32 vcc_lo, s90, 1
	s_sub_i32 s91, s89, s79
	s_cmp_ge_u32 s89, s79
	s_cselect_b32 s90, vcc_lo, s90
	s_cselect_b32 s89, s91, s89
	s_add_i32 s91, s90, 1
	ds_read_b128 v[2:5], v164
	s_cmp_ge_u32 s89, s79
	s_cselect_b32 s89, s91, s90
	s_xor_b32 s89, s89, s88
	s_sub_i32 s88, s89, s88
	s_mul_i32 s79, s88, s79
	s_lshl_b32 s88, s88, 6
	s_sub_i32 s79, s84, s79
	s_mul_hi_i32 s89, s88, s78
	s_mul_i32 s88, s88, s78
	s_lshl_b32 s90, s79, 6
	s_lshl_b64 s[88:89], s[88:89], 2
	s_add_u32 s79, s36, s88
	ds_read_b128 v[10:13], v103 offset:46080
	ds_read_b128 v[14:17], v164 offset:64
	ds_read_b128 v[30:33], v103 offset:36928
	ds_read_b128 v[38:41], v103 offset:46144
	ds_read_b128 v[42:45], v164 offset:128
	s_addc_u32 s84, s37, s89
	s_ashr_i32 s91, s90, 31
	s_waitcnt lgkmcnt(5)
	v_mfma_f32_16x16x32_bf16 v[6:9], v[2:5], v[6:9], 0
	s_lshl_b64 s[36:37], s[90:91], 2
	s_add_u32 s36, s79, s36
	s_addc_u32 s37, s84, s37
	s_waitcnt lgkmcnt(4)
	v_mfma_f32_16x16x32_bf16 v[10:13], v[2:5], v[10:13], 0
	global_load_dwordx4 v[2:5], v82, s[36:37]
	s_lshl_b32 s96, s78, 2
	v_lshl_add_u64 v[54:55], s[36:37], 0, v[82:83]
	s_waitcnt lgkmcnt(2)
	v_mfma_f32_16x16x32_bf16 v[6:9], v[14:17], v[30:33], v[6:9]
	ds_read_b128 v[30:33], v103 offset:36992
	ds_read_b128 v[46:49], v164 offset:192
	s_waitcnt lgkmcnt(3)
	v_mfma_f32_16x16x32_bf16 v[14:17], v[14:17], v[38:41], v[10:13]
	ds_read_b128 v[38:41], v103 offset:37056
	s_waitcnt lgkmcnt(2)
	v_mfma_f32_16x16x32_bf16 v[30:33], v[42:45], v[30:33], v[6:9]
	v_lshl_add_u64 v[10:11], v[54:55], 0, s[96:97]
	v_lshl_add_u64 v[58:59], v[10:11], 0, s[96:97]
	s_nop 0
	global_load_dwordx4 v[6:9], v[10:11], off
	s_nop 0
	global_load_dwordx4 v[10:13], v[58:59], off
	s_waitcnt lgkmcnt(0)
	v_mfma_f32_16x16x32_bf16 v[30:33], v[46:49], v[38:41], v[30:33]
	ds_read_b128 v[54:57], v103 offset:46208
	ds_read_b128 v[38:41], v103 offset:46272
	v_lshl_add_u64 v[58:59], v[58:59], 0, s[96:97]
	s_waitcnt lgkmcnt(1)
	v_mfma_f32_16x16x32_bf16 v[42:45], v[42:45], v[54:57], v[14:17]
	s_nop 2
	v_add_f32_e32 v29, v165, v30
	v_mul_f32_e32 v29, 0xbfb8aa3b, v29
	v_exp_f32_e32 v29, v29
	s_waitcnt lgkmcnt(0)
	v_mfma_f32_16x16x32_bf16 v[38:41], v[46:49], v[38:41], v[42:45]
	v_add_f32_e32 v31, v165, v31
	v_mul_f32_e32 v31, 0xbfb8aa3b, v31
	v_add_f32_e32 v14, 1.0, v29
	v_rcp_f32_e32 v29, v14
	v_exp_f32_e32 v31, v31
	global_load_dwordx4 v[14:17], v[58:59], off
	ds_read_u16 v42, v113
	ds_read_u16 v43, v113 offset:288
	ds_read_u16 v44, v113 offset:576
	ds_read_u16 v45, v113 offset:864
	v_mul_f32_e64 v29, v29, -v168
	v_exp_f32_e32 v70, v29
	v_add_f32_e32 v29, v167, v38
	v_mul_f32_e32 v29, 0xbfb8aa3b, v29
	v_exp_f32_e32 v29, v29
	v_fma_f32 v30, -v70, v70, 1.0
	s_nop 0
	s_nop 0
	v_add_f32_e32 v29, 1.0, v29
	v_rcp_f32_e32 v29, v29
	s_nop 0
	v_sqrt_f32_e32 v38, v30
	v_add_f32_e32 v31, 1.0, v31
	v_rcp_f32_e32 v31, v31
	v_add_f32_e32 v32, v165, v32
	v_add_u32_e32 v46, -1, v38
	v_fma_f32 v47, -v46, v38, v30
	v_cmp_ge_f32_e64 s[36:37], 0, v47
	v_add_u32_e32 v47, 1, v38
	v_mul_f32_e32 v32, 0xbfb8aa3b, v32
	v_cndmask_b32_e64 v46, v38, v46, s[36:37]
	v_fma_f32 v38, -v47, v38, v30
	v_cmp_lt_f32_e64 s[36:37], 0, v38
	v_exp_f32_e32 v32, v32
	v_add_f32_e32 v33, v165, v33
	v_cndmask_b32_e64 v38, v46, v47, s[36:37]
	s_nop 0
	s_nop 0
	s_nop 0
	v_add_f32_e32 v32, 1.0, v32
	v_rcp_f32_e32 v32, v32
	v_mov_b32_e32 v30, v38
	s_waitcnt lgkmcnt(3)
	v_lshlrev_b32_e32 v38, 16, v42
	v_mul_f32_e32 v29, v29, v38
	v_mul_f32_e32 v71, v29, v30
	v_mul_f32_e64 v29, v31, -v168
	v_exp_f32_e32 v72, v29
	v_add_f32_e32 v29, v167, v39
	v_mul_f32_e32 v29, 0xbfb8aa3b, v29
	v_exp_f32_e32 v29, v29
	v_fma_f32 v30, -v72, v72, 1.0
	s_nop 0
	s_nop 0
	v_add_f32_e32 v29, 1.0, v29
	v_rcp_f32_e32 v29, v29
	s_nop 0
	v_sqrt_f32_e32 v31, v30
	v_mul_f32_e32 v33, 0xbfb8aa3b, v33
	v_exp_f32_e32 v33, v33
	v_fma_f32 v38, 0, v70, v71
	v_add_u32_e32 v39, -1, v31
	v_fma_f32 v42, -v39, v31, v30
	v_cmp_ge_f32_e64 s[36:37], 0, v42
	v_add_u32_e32 v42, 1, v31
	v_add_f32_e32 v33, 1.0, v33
	v_cndmask_b32_e64 v39, v31, v39, s[36:37]
	v_fma_f32 v31, -v42, v31, v30
	v_cmp_lt_f32_e64 s[36:37], 0, v31
	v_rcp_f32_e32 v33, v33
	s_nop 0
	v_cndmask_b32_e64 v31, v39, v42, s[36:37]
	s_nop 0
	s_nop 0
	s_nop 0
	s_nop 1
	v_mov_b32_e32 v30, v31
	s_waitcnt lgkmcnt(2)
	v_lshlrev_b32_e32 v31, 16, v43
	v_mul_f32_e32 v29, v29, v31
	v_mul_f32_e32 v73, v29, v30
	v_mul_f32_e64 v30, v32, -v168
	v_exp_f32_e32 v74, v30
	v_add_f32_e32 v30, v167, v40
	v_mul_f32_e32 v30, 0xbfb8aa3b, v30
	v_exp_f32_e32 v30, v30
	v_fma_f32 v31, -v74, v74, 1.0
	s_nop 0
	s_nop 0
	v_add_f32_e32 v30, 1.0, v30
	v_rcp_f32_e32 v30, v30
	s_nop 0
	v_sqrt_f32_e32 v32, v31
	v_fma_f32 v29, v72, v38, v73
	v_mul_f32_e32 v38, v70, v72
	v_add_u32_e32 v39, -1, v32
	v_fma_f32 v40, -v39, v32, v31
	v_cmp_ge_f32_e64 s[36:37], 0, v40
	v_add_u32_e32 v40, 1, v32
	s_nop 0
	v_cndmask_b32_e64 v39, v32, v39, s[36:37]
	v_fma_f32 v32, -v40, v32, v31
	v_cmp_lt_f32_e64 s[36:37], 0, v32
	s_nop 1
	v_cndmask_b32_e64 v32, v39, v40, s[36:37]
	s_nop 0
	s_nop 0
	s_nop 0
	s_nop 1
	v_mov_b32_e32 v31, v32
	s_waitcnt lgkmcnt(1)
	v_lshlrev_b32_e32 v32, 16, v44
	v_mul_f32_e32 v30, v30, v32
	v_mul_f32_e32 v75, v30, v31
	v_fma_f32 v30, v74, v29, v75
	v_mul_f32_e64 v29, v33, -v168
	v_exp_f32_e32 v76, v29
	v_add_f32_e32 v29, v167, v41
	v_mul_f32_e32 v29, 0xbfb8aa3b, v29
	v_exp_f32_e32 v29, v29
	v_fma_f32 v31, -v76, v76, 1.0
	s_nop 0
	s_nop 0
	v_mul_f32_e32 v33, v74, v38
	v_add_f32_e32 v29, 1.0, v29
	s_nop 0
	v_sqrt_f32_e32 v32, v31
	v_rcp_f32_e32 v29, v29
	v_add_u32_e32 v38, -1, v32
	v_fma_f32 v39, -v38, v32, v31
	v_cmp_ge_f32_e64 s[36:37], 0, v39
	v_add_u32_e32 v39, 1, v32
	s_nop 0
	v_cndmask_b32_e64 v38, v32, v38, s[36:37]
	v_fma_f32 v32, -v39, v32, v31
	v_cmp_lt_f32_e64 s[36:37], 0, v32
	s_nop 1
	v_cndmask_b32_e64 v32, v38, v39, s[36:37]
	s_nop 0
	s_nop 0
	s_nop 0
	s_mov_b32 s36, 0x25300000
	s_nop 0
	v_mov_b32_e32 v31, v32
	s_waitcnt lgkmcnt(0)
	v_lshlrev_b32_e32 v32, 16, v45
	v_mul_f32_e32 v29, v29, v32
	v_mul_f32_e32 v29, v29, v31
	v_fma_f32 v30, v76, v30, v29
	v_mul_f32_e32 v31, v76, v33
	ds_write2st64_b32 v150, v31, v30 offset0:216 offset1:226
	s_waitcnt lgkmcnt(0)
	s_barrier
; #define LAS __attribute__((address_space(3)))
; DI float bf2f(unsigned h) { return __uint_as_float(h << 16); }
; DI unsigned pk2(float lo, float hi) { f32x2 v = {lo, hi}; bf16v2 b = __builtin_convertvector(v, bf16v2); return __builtin_bit_cast(unsigned, b); }
; DI float fsilu(float x) { return x * fsigmoid(x); }
; DI void rglru_scan_unit(Frame& F, const Mix0Args& a, int u) {
;     ...
;         float carry = HPREV[jj * 20 + (n & 1)]; float sa[15], sh[15];
;         { f32x4 a4[4], h4[4];
; #pragma unroll
;           for (int i = 0; i < 4; ++i) { a4[i] = *(const LAS f32x4*)(SEGA + jj * 20 + 4 * i); h4[i] = *(const LAS f32x4*)(SEGH + jj * 20 + 4 * i); }
; #pragma unroll
;           for (int s = 0; s < 15; ++s) { sa[s] = a4[s >> 2][s & 3]; sh[s] = h4[s >> 2][s & 3]; } }
; #pragma unroll
;         for (int s = 0; s < 15; ++s) carry = (s < sgi) ? sa[s] * carry + sh[s] : carry;
; #pragma unroll
;         for (int r = 0; r < 4; ++r) { carry = av[r] * carry + uv[r];
;             const float o = carry * fsilu(bf2f(gb_cur[r]));
;             obcol[(row0 + l0_ + 4 * fq + r) * a.out_ld] = (bf16)(pk2(o, 0.f) & 0xffffu); }
;         if (sgi == 15) HPREV[jj * 20 + ((n + 1) & 1)] = carry;
	ds_read_b32 v77, v149 offset:55360
	ds_read_b128 v[30:33], v149 offset:57856
	ds_read_b128 v[38:41], v149 offset:57872
	ds_read_b128 v[42:45], v149 offset:57888
	ds_read_b128 v[46:49], v149 offset:55296
	ds_read_b128 v[54:57], v149 offset:55312
	ds_read_b128 v[58:61], v149 offset:55328
	ds_read_b128 v[62:65], v149 offset:55344
	ds_read_b128 v[66:69], v149 offset:57904
	s_waitcnt lgkmcnt(4)
	v_fma_f32 v30, v77, v46, v30
	v_cndmask_b32_e64 v30, v30, v77, s[10:11]
	v_fma_f32 v31, v47, v30, v31
	v_cndmask_b32_e64 v30, v30, v31, s[12:13]
	v_fma_f32 v31, v48, v30, v32
	v_cndmask_b32_e64 v30, v30, v31, s[14:15]
	v_fmac_f32_e32 v33, v49, v30
	v_cndmask_b32_e64 v30, v33, v30, s[0:1]
	s_waitcnt lgkmcnt(3)
	v_fma_f32 v31, v54, v30, v38
	v_cndmask_b32_e64 v30, v30, v31, s[16:17]
	v_fma_f32 v31, v55, v30, v39
	v_cndmask_b32_e64 v30, v30, v31, s[18:19]
	v_fma_f32 v31, v56, v30, v40
	v_cndmask_b32_e64 v30, v30, v31, s[20:21]
	v_fmac_f32_e32 v41, v57, v30
	v_cndmask_b32_e64 v30, v30, v41, s[38:39]
	s_waitcnt lgkmcnt(2)
	v_fma_f32 v31, v58, v30, v42
	v_cndmask_b32_e64 v30, v30, v31, s[22:23]
	v_fma_f32 v31, v59, v30, v43
	v_cndmask_b32_e64 v30, v30, v31, s[24:25]
	v_fma_f32 v31, v60, v30, v44
	v_cndmask_b32_e64 v30, v30, v31, s[26:27]
	v_lshlrev_b32_e32 v32, 16, v181
	v_fmac_f32_e32 v45, v61, v30
	v_mul_f32_e32 v33, 0xbfb8aa3b, v32
	v_cndmask_b32_e64 v30, v30, v45, s[4:5]
	v_exp_f32_e32 v33, v33
	s_waitcnt lgkmcnt(0)
	v_fma_f32 v31, v62, v30, v66
	v_cndmask_b32_e64 v30, v30, v31, s[28:29]
	v_fma_f32 v31, v63, v30, v67
	v_cndmask_b32_e64 v30, v30, v31, s[30:31]
	v_add_f32_e32 v31, 1.0, v33
	v_rcp_f32_e32 v31, v31
	v_fmac_f32_e32 v68, v64, v30
	v_cndmask_b32_e64 v30, v30, v68, s[34:35]
	v_fmac_f32_e32 v71, v70, v30
	v_mul_f32_e32 v30, v31, v32
	v_mul_f32_e32 v30, v30, v71
	v_lshlrev_b32_e32 v33, 16, v180
	v_cvt_pk_bf16_f32 v32, v30, s0
	v_mul_f32_e32 v30, 0xbfb8aa3b, v33
	v_exp_f32_e32 v38, v30
	v_lshl_add_u64 v[66:67], v[116:117], 0, s[8:9]
	v_add_co_u32_e32 v30, vcc, s36, v66
	v_fmac_f32_e32 v73, v72, v71
	s_nop 0
	v_addc_co_u32_e32 v31, vcc, 0, v67, vcc
	global_store_short v[30:31], v32, off
	v_add_f32_e32 v30, 1.0, v38
	v_rcp_f32_e32 v30, v30
	v_lshlrev_b32_e32 v32, 16, v179
	v_mul_f32_e32 v31, 0xbfb8aa3b, v32
	v_exp_f32_e32 v31, v31
	v_mul_f32_e32 v30, v30, v33
	v_mul_f32_e32 v30, v30, v73
	v_cvt_pk_bf16_f32 v33, v30, s0
	v_add_f32_e32 v30, 1.0, v31
	v_rcp_f32_e32 v38, v30
	s_mov_b32 s36, 0x2530c000
	v_add_co_u32_e32 v30, vcc, s36, v66
	v_fmac_f32_e32 v75, v74, v73
	s_nop 0
	v_addc_co_u32_e32 v31, vcc, 0, v67, vcc
	global_store_short v[30:31], v33, off
	v_mul_f32_e32 v30, v38, v32
	v_lshlrev_b32_e32 v32, 16, v178
	v_mul_f32_e32 v31, 0xbfb8aa3b, v32
	v_exp_f32_e32 v31, v31
	v_mul_f32_e32 v30, v30, v75
	s_mov_b32 s36, 0x25318000
	v_cvt_pk_bf16_f32 v33, v30, s0
	v_add_f32_e32 v31, 1.0, v31
	v_rcp_f32_e32 v38, v31
	v_add_co_u32_e32 v30, vcc, s36, v66
	v_fmac_f32_e32 v29, v76, v75
	s_nop 0
	v_addc_co_u32_e32 v31, vcc, 0, v67, vcc
	global_store_short v[30:31], v33, off
	v_mul_f32_e32 v30, v38, v32
	v_mul_f32_e32 v30, v30, v29
	v_cvt_pk_bf16_f32 v32, v30, s0
	s_mov_b64 s[100:101], 0x25324000
	v_lshl_add_u64 v[30:31], v[66:67], 0, s[100:101]
	global_store_short v[30:31], v32, off
	s_and_saveexec_b64 s[36:37], s[34:35]
	ds_write_b32 v149, v29 offset:55364
	s_or_b64 exec, exec, s[36:37]
	s_waitcnt vmcnt(22)
	v_lshlrev_b32_e32 v30, 16, v18
	v_and_b32_e32 v31, 0xffff0000, v18
	v_pk_fma_f32 v[30:31], v[104:105], v[30:31], v[100:101]
	s_waitcnt vmcnt(21)
	v_lshlrev_b32_e32 v18, 16, v19
	v_and_b32_e32 v19, 0xffff0000, v19
	v_pk_fma_f32 v[30:31], v[106:107], v[18:19], v[30:31]
	s_waitcnt vmcnt(20)
	v_lshlrev_b32_e32 v32, 16, v20
	v_and_b32_e32 v33, 0xffff0000, v20
	v_pk_fma_f32 v[30:31], v[108:109], v[32:33], v[30:31]
	s_waitcnt vmcnt(19)
	v_lshlrev_b32_e32 v20, 16, v21
	v_and_b32_e32 v21, 0xffff0000, v21
	v_pk_fma_f32 v[18:19], v[104:105], v[18:19], v[100:101]
	v_pk_fma_f32 v[30:31], v[110:111], v[20:21], v[30:31]
	v_pk_fma_f32 v[18:19], v[106:107], v[32:33], v[18:19]
	v_cvt_pk_bf16_f32 v29, v30, v31
	v_pk_fma_f32 v[18:19], v[108:109], v[20:21], v[18:19]
	s_waitcnt vmcnt(18)
	v_lshlrev_b32_e32 v30, 16, v22
	v_and_b32_e32 v31, 0xffff0000, v22
	v_pk_fma_f32 v[18:19], v[110:111], v[30:31], v[18:19]
	s_waitcnt vmcnt(17)
	v_lshlrev_b32_e32 v22, 16, v23
	v_cvt_pk_bf16_f32 v18, v18, v19
	ds_write2_b32 v123, v29, v18 offset1:72
	v_pk_fma_f32 v[18:19], v[104:105], v[32:33], v[100:101]
	v_and_b32_e32 v23, 0xffff0000, v23
	v_pk_fma_f32 v[18:19], v[106:107], v[20:21], v[18:19]
	v_add_u32_e32 v54, 0x400, v123
	v_pk_fma_f32 v[18:19], v[108:109], v[30:31], v[18:19]
	s_mov_b32 s36, 0x25be4000
	v_pk_fma_f32 v[18:19], v[110:111], v[22:23], v[18:19]
	s_nop 0
	v_cvt_pk_bf16_f32 v29, v18, v19
	v_pk_fma_f32 v[18:19], v[104:105], v[20:21], v[100:101]
	s_waitcnt vmcnt(16)
	v_lshlrev_b32_e32 v20, 16, v24
	v_pk_fma_f32 v[18:19], v[106:107], v[30:31], v[18:19]
	v_and_b32_e32 v21, 0xffff0000, v24
	v_pk_fma_f32 v[18:19], v[108:109], v[22:23], v[18:19]
	s_nop 0
	v_pk_fma_f32 v[18:19], v[110:111], v[20:21], v[18:19]
	s_nop 0
	v_cvt_pk_bf16_f32 v18, v18, v19
	ds_write2_b32 v123, v29, v18 offset0:144 offset1:216
	v_pk_fma_f32 v[18:19], v[104:105], v[30:31], v[100:101]
	s_waitcnt vmcnt(15)
	v_lshlrev_b32_e32 v30, 16, v27
	v_pk_fma_f32 v[18:19], v[106:107], v[22:23], v[18:19]
	v_and_b32_e32 v31, 0xffff0000, v27
	v_pk_fma_f32 v[18:19], v[108:109], v[20:21], v[18:19]
	s_nop 0
	v_pk_fma_f32 v[18:19], v[110:111], v[30:31], v[18:19]
	s_nop 0
	v_cvt_pk_bf16_f32 v24, v18, v19
	v_pk_fma_f32 v[18:19], v[104:105], v[22:23], v[100:101]
	s_waitcnt vmcnt(14)
	v_lshlrev_b32_e32 v22, 16, v25
	v_pk_fma_f32 v[18:19], v[106:107], v[20:21], v[18:19]
	v_and_b32_e32 v23, 0xffff0000, v25
	v_pk_fma_f32 v[18:19], v[108:109], v[30:31], v[18:19]
	s_nop 0
	v_pk_fma_f32 v[18:19], v[110:111], v[22:23], v[18:19]
	s_nop 0
	v_cvt_pk_bf16_f32 v18, v18, v19
	ds_write2_b32 v54, v24, v18 offset0:32 offset1:104
	v_pk_fma_f32 v[18:19], v[104:105], v[20:21], v[100:101]
	s_waitcnt vmcnt(13)
	v_lshlrev_b32_e32 v20, 16, v26
	v_pk_fma_f32 v[18:19], v[106:107], v[30:31], v[18:19]
	v_and_b32_e32 v21, 0xffff0000, v26
	v_pk_fma_f32 v[18:19], v[108:109], v[22:23], v[18:19]
	s_nop 0
	v_pk_fma_f32 v[18:19], v[110:111], v[20:21], v[18:19]
	s_nop 0
	v_cvt_pk_bf16_f32 v24, v18, v19
	v_pk_fma_f32 v[18:19], v[104:105], v[30:31], v[100:101]
	s_nop 0
	v_pk_fma_f32 v[18:19], v[106:107], v[22:23], v[18:19]
	s_nop 0
	v_pk_fma_f32 v[18:19], v[108:109], v[20:21], v[18:19]
	s_waitcnt vmcnt(12)
	v_lshlrev_b32_e32 v20, 16, v28
	v_and_b32_e32 v21, 0xffff0000, v28
	v_pk_fma_f32 v[18:19], v[110:111], v[20:21], v[18:19]
	s_nop 0
	v_cvt_pk_bf16_f32 v18, v18, v19
	ds_write2_b32 v54, v24, v18 offset0:176 offset1:248
	v_add_co_u32_e32 v18, vcc, s36, v50
	s_mov_b32 s36, 0x25bf0000
	s_nop 0
	v_addc_co_u32_e32 v19, vcc, 0, v51, vcc
	global_load_dword v130, v[18:19], off
	v_add_co_u32_e32 v18, vcc, s36, v50
	s_mov_b32 s36, 0x25bfc000
	s_nop 0
	v_addc_co_u32_e32 v19, vcc, 0, v51, vcc
	global_load_dword v132, v[18:19], off
	v_add_co_u32_e32 v18, vcc, s36, v50
	s_mov_b32 s36, 0x25c08000
	s_nop 0
	v_addc_co_u32_e32 v19, vcc, 0, v51, vcc
	global_load_dword v134, v[18:19], off
	v_add_co_u32_e32 v18, vcc, s36, v50
	s_mov_b32 s36, 0x25c14000
	s_nop 0
	v_addc_co_u32_e32 v19, vcc, 0, v51, vcc
	global_load_dword v169, v[18:19], off
	v_add_co_u32_e32 v18, vcc, s36, v50
	s_mov_b32 s36, 0x25c20000
	s_nop 0
	v_addc_co_u32_e32 v19, vcc, 0, v51, vcc
	global_load_dword v170, v[18:19], off
	v_add_co_u32_e32 v18, vcc, s36, v50
	s_mov_b32 s36, 0x25c2c000
	s_nop 0
	v_addc_co_u32_e32 v19, vcc, 0, v51, vcc
	global_load_dword v171, v[18:19], off
	v_add_co_u32_e32 v18, vcc, s36, v50
	s_mov_b32 s36, 0x25c38000
	s_nop 0
	v_addc_co_u32_e32 v19, vcc, 0, v51, vcc
	global_load_dword v172, v[18:19], off
	v_add_co_u32_e32 v18, vcc, s36, v50
	s_mov_b32 s36, 0x25c44000
	s_nop 0
	v_addc_co_u32_e32 v19, vcc, 0, v51, vcc
	global_load_dword v173, v[18:19], off
	v_add_co_u32_e32 v18, vcc, s36, v50
	s_mov_b32 s36, 0x25c50000
	s_nop 0
	v_addc_co_u32_e32 v19, vcc, 0, v51, vcc
	global_load_dword v174, v[18:19], off
	v_add_co_u32_e32 v18, vcc, s36, v50
	s_mov_b32 s36, 0x25c5c000
	s_nop 0
	v_addc_co_u32_e32 v19, vcc, 0, v51, vcc
	global_load_dword v175, v[18:19], off
	v_add_co_u32_e32 v18, vcc, s36, v50
	s_mov_b32 s36, 0x2590a000
	s_nop 0
	v_addc_co_u32_e32 v19, vcc, 0, v51, vcc
	global_load_dword v176, v[18:19], off
	v_add_co_u32_e32 v18, vcc, s36, v52
	s_nop 1
	v_addc_co_u32_e32 v19, vcc, 0, v53, vcc
	global_load_ushort v58, v[18:19], off
	s_nop 0
	s_nop 0
	s_nop 0
	v_readfirstlane_b32 s98, v52
	v_readfirstlane_b32 s99, v53
	s_add_u32 s100, s98, 0x25916000
	s_addc_u32 s101, s99, 0x0
	global_load_ushort v56, v209, s[100:101]
	s_nop 0
	s_nop 0
	s_add_u32 s100, s98, 0x25922000
	s_addc_u32 s101, s99, 0x0
	global_load_ushort v55, v209, s[100:101]
	s_nop 0
	s_nop 0
	s_add_u32 s100, s98, 0x2592e000
	s_addc_u32 s101, s99, 0x0
	global_load_ushort v57, v209, s[100:101]
	v_cndmask_b32_e64 v18, 0, 1, s[40:41]
	v_cmp_ne_u32_e64 s[36:37], 1, v18
	s_andn2_b64 vcc, exec, s[40:41]
	s_cbranch_vccnz .LBB0_274
	s_cmpk_gt_u32 s87, 0x687f
	s_cbranch_scc0 .LBB0_275
	s_add_i32 s84, s87, 0xffff9780
	s_mov_b64 s[40:41], s[52:53]
	s_movk_i32 s78, 0x1000
	s_cbranch_execz .LBB0_276
	s_branch .LBB0_277

; #define LAS __attribute__((address_space(3)))
; DI float bf2f(unsigned h) { return __uint_as_float(h << 16); }
; DI float fexp2(float x) { return __builtin_amdgcn_exp2f(x); }
; DI float fsigmoid(float x) { return frcp(1.0f + fexp2(-LOG2E * x)); }
; DI void cv_issue_q(const CvJob& j, int idx, int lane, f32x4 (&v)[4], int r0) {
;     const float* W; int K, N, item; bf16* WT; const float* ks; cv_decode(j, idx, W, K, N, WT, ks, item);
;     const int nblk = N / 64, kb = item / nblk, nb = item % nblk, k0 = 64 * kb, n0 = 64 * nb, q = lane >> 4, c16 = lane & 15;
;     const char* ub = (const char*)(W + (size_t)(k0 + r0) * N + n0);
;     const unsigned vo = (unsigned)((16 * q) * N + 4 * c16) * 4u;
; #pragma unroll
;     for (int i = 0; i < 4; ++i) v[i] = *(const f32x4*)(ub + (size_t)i * N * 4 + vo);
; }
; DI void rglru_scan_unit(Frame& F, const Mix0Args& a, int u) {
;     ...
;         { bf16x8 xf[4], waf[4], wxf[4]; unsigned xcr[4];
; #pragma unroll
;           for (int ks = 0; ks < 4; ++ks) { xf[ks] = *(const LAS bf16x8*)(XCc + (l0_ + fr) * S128 + ks * 64 + fq * 16);
;               waf[ks] = *(const LAS bf16x8*)(WAT + (16 * jtile + fr) * S128 + ks * 64 + fq * 16); wxf[ks] = *(const LAS bf16x8*)(WXT + (16 * jtile + fr) * S128 + ks * 64 + fq * 16); }
; #pragma unroll
;           for (int r = 0; r < 4; ++r) xcr[r] = *(const LAS unsigned short*)(XCc + (l0_ + 4 * fq + r) * S128 + (qq * 32 + jj) * 2);
;           f32x4 R = zero4, I = zero4;
; #pragma unroll
;           for (int ks = 0; ks < 4; ++ks) { R = __builtin_amdgcn_mfma_f32_16x16x32_bf16(xf[ks], waf[ks], R, 0, 0, 0); I = __builtin_amdgcn_mfma_f32_16x16x32_bf16(xf[ks], wxf[ks], I, 0, 0, 0); }
; #pragma unroll
;           for (int r = 0; r < 4; ++r) {
;               const float rr = fsigmoid(R[r] + bav), ig = fsigmoid(I[r] + bxv);
;               const float aa = fexp2(-sp8l2 * rr); const float om = __builtin_fmaf(-aa, aa, 1.0f);
;               av[r] = aa; uv[r] = __builtin_sqrtf(om) * (ig * bf2f(xcr[r]));
;               Hseg = aa * Hseg + uv[r]; Aseg *= aa; } }
;         const int sgi = ltile * 4 + fq;
;         SEGA[jj * 20 + sgi] = Aseg; SEGH[jj * 20 + sgi] = Hseg;
.LBB0_277:
	s_lshr_b32 s79, s78, 6
	v_cvt_f32_u32_e32 v18, s79
	s_sub_i32 s90, 0, s79
	s_abs_i32 s89, s84
	s_ashr_i32 s88, s84, 31
	v_rcp_iflag_f32_e32 v18, v18
	v_mul_u32_u24_e32 v42, s78, v102
	v_or_b32_e32 v42, v42, v125
	v_lshlrev_b32_e32 v82, 2, v42
	v_mul_f32_e32 v18, 0x4f7ffffe, v18
	v_cvt_u32_f32_e32 v18, v18
	s_waitcnt vmcnt(26)
	v_lshlrev_b32_e32 v37, 16, v37
	s_waitcnt vmcnt(24)
	v_lshlrev_b32_e32 v34, 16, v34
	ds_read_b128 v[22:25], v103 offset:36864
	v_readfirstlane_b32 s91, v18
	s_mul_i32 s90, s90, s91
	s_mul_hi_u32 s90, s91, s90
	s_add_i32 s91, s91, s90
	s_mul_hi_u32 s90, s89, s91
	s_mul_i32 s91, s90, s79
	s_sub_i32 s89, s89, s91
	s_add_i32 vcc_lo, s90, 1
	s_sub_i32 s91, s89, s79
	s_cmp_ge_u32 s89, s79
	s_cselect_b32 s90, vcc_lo, s90
	s_cselect_b32 s89, s91, s89
	s_add_i32 s91, s90, 1
	s_cmp_ge_u32 s89, s79
	ds_read_b128 v[18:21], v164 offset:18432
	s_cselect_b32 s89, s91, s90
	s_xor_b32 s89, s89, s88
	s_sub_i32 s88, s89, s88
	s_mul_i32 s79, s88, s79
	s_lshl_b32 s88, s88, 6
	s_sub_i32 s79, s84, s79
	s_or_b32 s84, s88, 4
	s_mul_hi_i32 s91, s84, s78
	s_mul_i32 s90, s84, s78
	s_lshl_b32 s88, s79, 6
	s_lshl_b64 s[90:91], s[90:91], 2
	s_add_u32 s79, s40, s90
	ds_read_b128 v[26:29], v103 offset:46080
	ds_read_b128 v[30:33], v164 offset:18496
	ds_read_b128 v[38:41], v103 offset:36928
	ds_read_b128 v[42:45], v103 offset:46144
	ds_read_b128 v[46:49], v164 offset:18560
	s_addc_u32 s84, s41, s91
	s_ashr_i32 s89, s88, 31
	s_waitcnt lgkmcnt(5)
	v_mfma_f32_16x16x32_bf16 v[22:25], v[18:21], v[22:25], 0
	s_lshl_b64 s[40:41], s[88:89], 2
	s_add_u32 s40, s79, s40
	s_addc_u32 s41, s84, s41
	s_waitcnt lgkmcnt(4)
	v_mfma_f32_16x16x32_bf16 v[26:29], v[18:21], v[26:29], 0
	global_load_dwordx4 v[18:21], v82, s[40:41]
	s_lshl_b32 s96, s78, 2
	v_lshl_add_u64 v[64:65], s[40:41], 0, v[82:83]
	s_waitcnt lgkmcnt(2)
	v_mfma_f32_16x16x32_bf16 v[22:25], v[30:33], v[38:41], v[22:25]
	ds_read_b128 v[38:41], v103 offset:36992
	ds_read_b128 v[60:63], v164 offset:18624
	s_waitcnt lgkmcnt(3)
	v_mfma_f32_16x16x32_bf16 v[30:33], v[30:33], v[42:45], v[26:29]
	ds_read_b128 v[42:45], v103 offset:37056
	s_waitcnt lgkmcnt(2)
	v_mfma_f32_16x16x32_bf16 v[38:41], v[46:49], v[38:41], v[22:25]
	v_lshl_add_u64 v[26:27], v[64:65], 0, s[96:97]
	v_lshl_add_u64 v[64:65], v[26:27], 0, s[96:97]
	s_nop 0
	global_load_dwordx4 v[22:25], v[26:27], off
	s_nop 0
	global_load_dwordx4 v[26:29], v[64:65], off
	s_waitcnt lgkmcnt(0)
	v_mfma_f32_16x16x32_bf16 v[38:41], v[60:63], v[42:45], v[38:41]
	ds_read_b128 v[68:71], v103 offset:46208
	ds_read_b128 v[42:45], v103 offset:46272
	v_lshl_add_u64 v[64:65], v[64:65], 0, s[96:97]
	s_waitcnt lgkmcnt(1)
	v_mfma_f32_16x16x32_bf16 v[46:49], v[46:49], v[68:71], v[30:33]
	s_nop 2
	v_add_f32_e32 v38, v165, v38
	v_mul_f32_e32 v38, 0xbfb8aa3b, v38
	v_exp_f32_e32 v38, v38
	s_waitcnt lgkmcnt(0)
	v_mfma_f32_16x16x32_bf16 v[42:45], v[60:63], v[42:45], v[46:49]
	v_add_f32_e32 v39, v165, v39
	v_mul_f32_e32 v39, 0xbfb8aa3b, v39
	v_add_f32_e32 v30, 1.0, v38
	v_rcp_f32_e32 v38, v30
	v_exp_f32_e32 v39, v39
	global_load_dwordx4 v[30:33], v[64:65], off
	ds_read_u16 v47, v177 offset:18432
	ds_read_u16 v49, v177 offset:18720
	ds_read_u16 v59, v177 offset:19008
	ds_read_u16 v60, v177 offset:19296
	v_mul_f32_e64 v38, v38, -v168
	v_exp_f32_e32 v48, v38
	v_add_f32_e32 v38, v167, v42
	v_mul_f32_e32 v38, 0xbfb8aa3b, v38
	v_exp_f32_e32 v38, v38
	v_fma_f32 v42, -v48, v48, 1.0
	s_nop 0
	s_nop 0
	v_add_f32_e32 v38, 1.0, v38
	v_rcp_f32_e32 v38, v38
	s_nop 0
	v_sqrt_f32_e32 v46, v42
	v_add_f32_e32 v39, 1.0, v39
	v_rcp_f32_e32 v39, v39
	v_add_f32_e32 v40, v165, v40
	v_add_u32_e32 v61, -1, v46
	v_fma_f32 v62, -v61, v46, v42
	v_cmp_ge_f32_e64 s[40:41], 0, v62
	v_add_u32_e32 v62, 1, v46
	v_mul_f32_e32 v40, 0xbfb8aa3b, v40
	v_cndmask_b32_e64 v61, v46, v61, s[40:41]
	v_fma_f32 v46, -v62, v46, v42
	v_cmp_lt_f32_e64 s[40:41], 0, v46
	v_exp_f32_e32 v40, v40
	v_add_f32_e32 v41, v165, v41
	v_cndmask_b32_e64 v46, v61, v62, s[40:41]
	s_nop 0
	s_nop 0
	s_nop 0
	v_add_f32_e32 v40, 1.0, v40
	v_rcp_f32_e32 v40, v40
	v_mov_b32_e32 v42, v46
	s_waitcnt lgkmcnt(3)
	v_lshlrev_b32_e32 v46, 16, v47
	v_mul_f32_e32 v38, v38, v46
	v_mul_f32_e32 v64, v38, v42
	v_mul_f32_e64 v38, v39, -v168
	v_exp_f32_e32 v39, v38
	v_add_f32_e32 v38, v167, v43
	v_mul_f32_e32 v38, 0xbfb8aa3b, v38
	v_exp_f32_e32 v38, v38
	v_fma_f32 v42, -v39, v39, 1.0
	s_nop 0
	s_nop 0
	v_add_f32_e32 v38, 1.0, v38
	v_rcp_f32_e32 v38, v38
	s_nop 0
	v_sqrt_f32_e32 v43, v42
	v_mul_f32_e64 v40, v40, -v168
	v_exp_f32_e32 v65, v40
	v_add_f32_e32 v40, v167, v44
	v_add_u32_e32 v47, -1, v43
	v_fma_f32 v61, -v47, v43, v42
	v_cmp_ge_f32_e64 s[40:41], 0, v61
	v_add_u32_e32 v61, 1, v43
	v_fma_f32 v46, 0, v48, v64
	v_cndmask_b32_e64 v47, v43, v47, s[40:41]
	v_fma_f32 v43, -v61, v43, v42
	v_cmp_lt_f32_e64 s[40:41], 0, v43
	v_mul_f32_e32 v40, 0xbfb8aa3b, v40
	v_exp_f32_e32 v40, v40
	v_cndmask_b32_e64 v43, v47, v61, s[40:41]
	s_nop 0
	s_nop 0
	s_nop 0
	v_mul_f32_e32 v41, 0xbfb8aa3b, v41
	v_exp_f32_e32 v41, v41
	v_mov_b32_e32 v42, v43
	s_waitcnt lgkmcnt(2)
	v_lshlrev_b32_e32 v43, 16, v49
	v_mul_f32_e32 v38, v38, v43
	v_mul_f32_e32 v49, v38, v42
	v_fma_f32 v42, -v65, v65, 1.0
	s_nop 0
	s_nop 0
	v_fma_f32 v38, v39, v46, v49
	v_add_f32_e32 v40, 1.0, v40
	s_nop 0
	v_sqrt_f32_e32 v43, v42
	v_rcp_f32_e32 v40, v40
	v_add_f32_e32 v41, 1.0, v41
	v_rcp_f32_e32 v41, v41
	v_add_u32_e32 v46, -1, v43
	v_fma_f32 v47, -v46, v43, v42
	v_cmp_ge_f32_e64 s[40:41], 0, v47
	v_add_u32_e32 v47, 1, v43
	v_mul_f32_e32 v44, v48, v39
	v_cndmask_b32_e64 v46, v43, v46, s[40:41]
	v_fma_f32 v43, -v47, v43, v42
	v_cmp_lt_f32_e64 s[40:41], 0, v43
	s_nop 1
	v_cndmask_b32_e64 v43, v46, v47, s[40:41]
	s_nop 0
	s_nop 0
	s_nop 0
	s_nop 1
	v_mov_b32_e32 v42, v43
	s_waitcnt lgkmcnt(1)
	v_lshlrev_b32_e32 v43, 16, v59
	v_mul_f32_e32 v40, v40, v43
	v_mul_f32_e32 v59, v40, v42
	v_fma_f32 v40, v65, v38, v59
	v_mul_f32_e64 v38, v41, -v168
	v_exp_f32_e32 v80, v38
	v_add_f32_e32 v38, v167, v45
	v_mul_f32_e32 v38, 0xbfb8aa3b, v38
	v_exp_f32_e32 v38, v38
	v_fma_f32 v41, -v80, v80, 1.0
	s_nop 0
	s_nop 0
	v_mul_f32_e32 v43, v65, v44
	v_add_f32_e32 v38, 1.0, v38
	s_nop 0
	v_sqrt_f32_e32 v42, v41
	v_rcp_f32_e32 v38, v38
	v_add_u32_e32 v44, -1, v42
	v_fma_f32 v45, -v44, v42, v41
	v_cmp_ge_f32_e64 s[40:41], 0, v45
	v_add_u32_e32 v45, 1, v42
	s_nop 0
	v_cndmask_b32_e64 v44, v42, v44, s[40:41]
	v_fma_f32 v42, -v45, v42, v41
	v_cmp_lt_f32_e64 s[40:41], 0, v42
	s_nop 1
	v_cndmask_b32_e64 v42, v44, v45, s[40:41]
	s_nop 0
	s_nop 0
	s_nop 0
	s_mov_b32 s40, 0x25600000
	s_nop 0
	v_mov_b32_e32 v41, v42
	s_waitcnt lgkmcnt(0)
	v_lshlrev_b32_e32 v42, 16, v60
	v_mul_f32_e32 v38, v38, v42
	v_mul_f32_e32 v38, v38, v41
	v_fma_f32 v40, v80, v40, v38
	v_mul_f32_e32 v41, v80, v43
	ds_write2st64_b32 v150, v41, v40 offset0:236 offset1:246
	s_waitcnt lgkmcnt(0)
	s_barrier
; #define LAS __attribute__((address_space(3)))
; DI float bf2f(unsigned h) { return __uint_as_float(h << 16); }
; DI unsigned pk2(float lo, float hi) { f32x2 v = {lo, hi}; bf16v2 b = __builtin_convertvector(v, bf16v2); return __builtin_bit_cast(unsigned, b); }
; DI float fsilu(float x) { return x * fsigmoid(x); }
; DI void rglru_scan_unit(Frame& F, const Mix0Args& a, int u) {
;     ...
;         float carry = HPREV[jj * 20 + (n & 1)]; float sa[15], sh[15];
;         { f32x4 a4[4], h4[4];
; #pragma unroll
;           for (int i = 0; i < 4; ++i) { a4[i] = *(const LAS f32x4*)(SEGA + jj * 20 + 4 * i); h4[i] = *(const LAS f32x4*)(SEGH + jj * 20 + 4 * i); }
; #pragma unroll
;           for (int s = 0; s < 15; ++s) { sa[s] = a4[s >> 2][s & 3]; sh[s] = h4[s >> 2][s & 3]; } }
; #pragma unroll
;         for (int s = 0; s < 15; ++s) carry = (s < sgi) ? sa[s] * carry + sh[s] : carry;
; #pragma unroll
;         for (int r = 0; r < 4; ++r) { carry = av[r] * carry + uv[r];
;             const float o = carry * fsilu(bf2f(gb_cur[r]));
;             obcol[(row0 + l0_ + 4 * fq + r) * a.out_ld] = (bf16)(pk2(o, 0.f) & 0xffffu); }
;         if (sgi == 15) HPREV[jj * 20 + ((n + 1) & 1)] = carry;
	ds_read_b32 v81, v149 offset:55364
	ds_read_b128 v[40:43], v149 offset:60416
	ds_read_b128 v[44:47], v149 offset:62976
	ds_read_b128 v[60:63], v149 offset:60432
	ds_read_b128 v[68:71], v149 offset:60448
	ds_read_b128 v[72:75], v149 offset:62992
	ds_read_b128 v[76:79], v149 offset:63008
	ds_read_b128 v[178:181], v149 offset:60464
	ds_read_b128 v[184:187], v149 offset:63024
	s_waitcnt lgkmcnt(6)
	v_fma_f32 v40, v81, v40, v44
	v_cndmask_b32_e64 v40, v40, v81, s[10:11]
	v_fma_f32 v41, v41, v40, v45
	v_cndmask_b32_e64 v40, v40, v41, s[12:13]
	v_fma_f32 v41, v42, v40, v46
	v_cndmask_b32_e64 v40, v40, v41, s[14:15]
	v_fmac_f32_e32 v47, v43, v40
	v_cndmask_b32_e64 v40, v47, v40, s[0:1]
	s_waitcnt lgkmcnt(3)
	v_fma_f32 v41, v60, v40, v72
	v_cndmask_b32_e64 v40, v40, v41, s[16:17]
	v_fma_f32 v41, v61, v40, v73
	v_cndmask_b32_e64 v40, v40, v41, s[18:19]
	v_fma_f32 v41, v62, v40, v74
	v_cndmask_b32_e64 v40, v40, v41, s[20:21]
	v_fmac_f32_e32 v75, v63, v40
	v_cndmask_b32_e64 v40, v40, v75, s[38:39]
	s_waitcnt lgkmcnt(2)
	v_fma_f32 v41, v68, v40, v76
	v_cndmask_b32_e64 v40, v40, v41, s[22:23]
	v_fma_f32 v41, v69, v40, v77
	v_cndmask_b32_e64 v40, v40, v41, s[24:25]
	v_fma_f32 v41, v70, v40, v78
	v_cndmask_b32_e64 v40, v40, v41, s[26:27]
	v_fmac_f32_e32 v79, v71, v40
	v_mul_f32_e32 v42, 0xbfb8aa3b, v37
	v_cndmask_b32_e64 v40, v40, v79, s[4:5]
	v_exp_f32_e32 v42, v42
	s_waitcnt lgkmcnt(0)
	v_fma_f32 v41, v178, v40, v184
	v_cndmask_b32_e64 v40, v40, v41, s[28:29]
	v_fma_f32 v41, v179, v40, v185
	v_cndmask_b32_e64 v40, v40, v41, s[30:31]
	v_add_f32_e32 v41, 1.0, v42
	v_rcp_f32_e32 v41, v41
	v_fmac_f32_e32 v186, v180, v40
	v_cndmask_b32_e64 v40, v40, v186, s[34:35]
	v_fmac_f32_e32 v64, v48, v40
	v_mul_f32_e32 v37, v41, v37
	v_lshlrev_b32_e32 v41, 16, v36
	v_mul_f32_e32 v36, 0xbfb8aa3b, v41
	v_exp_f32_e32 v42, v36
	v_mul_f32_e32 v37, v37, v64
	v_add_co_u32_e32 v36, vcc, s40, v66
	v_cvt_pk_bf16_f32 v40, v37, s0
	s_nop 0
	v_addc_co_u32_e32 v37, vcc, 0, v67, vcc
	global_store_short v[36:37], v40, off
	v_add_f32_e32 v36, 1.0, v42
	v_rcp_f32_e32 v36, v36
	v_mul_f32_e32 v37, 0xbfb8aa3b, v34
	v_exp_f32_e32 v37, v37
	v_fmac_f32_e32 v49, v39, v64
	v_mul_f32_e32 v36, v36, v41
	v_mul_f32_e32 v36, v36, v49
	v_cvt_pk_bf16_f32 v39, v36, s0
	v_add_f32_e32 v36, 1.0, v37
	s_mov_b32 s40, 0x2560c000
	v_rcp_f32_e32 v40, v36
	v_add_co_u32_e32 v36, vcc, s40, v66
	v_fmac_f32_e32 v59, v65, v49
	s_nop 0
	v_addc_co_u32_e32 v37, vcc, 0, v67, vcc
	global_store_short v[36:37], v39, off
	s_waitcnt vmcnt(29)
	v_lshlrev_b32_e32 v36, 16, v35
	v_mul_f32_e32 v35, 0xbfb8aa3b, v36
	v_exp_f32_e32 v35, v35
	v_mul_f32_e32 v34, v40, v34
	v_mul_f32_e32 v34, v34, v59
	s_mov_b32 s40, 0x25618000
	v_add_f32_e32 v35, 1.0, v35
	v_rcp_f32_e32 v39, v35
	v_cvt_pk_bf16_f32 v37, v34, s0
	v_add_co_u32_e32 v34, vcc, s40, v66
	v_fmac_f32_e32 v38, v80, v59
	s_nop 0
	v_addc_co_u32_e32 v35, vcc, 0, v67, vcc
	global_store_short v[34:35], v37, off
	v_mul_f32_e32 v34, v39, v36
	v_mul_f32_e32 v34, v34, v38
	v_cvt_pk_bf16_f32 v36, v34, s0
	s_mov_b64 s[100:101], 0x25624000
	v_lshl_add_u64 v[34:35], v[66:67], 0, s[100:101]
	global_store_short v[34:35], v36, off
	s_and_saveexec_b64 s[40:41], s[34:35]
	ds_write_b32 v149, v38 offset:55360
	s_or_b64 exec, exec, s[40:41]
	s_waitcnt vmcnt(22)
	v_lshlrev_b32_e32 v34, 16, v130
	v_and_b32_e32 v35, 0xffff0000, v130
	v_pk_fma_f32 v[34:35], v[104:105], v[34:35], v[100:101]
	s_waitcnt vmcnt(21)
	v_lshlrev_b32_e32 v36, 16, v132
	v_and_b32_e32 v37, 0xffff0000, v132
	v_pk_fma_f32 v[34:35], v[106:107], v[36:37], v[34:35]
	s_waitcnt vmcnt(20)
	v_lshlrev_b32_e32 v38, 16, v134
	v_and_b32_e32 v39, 0xffff0000, v134
	v_pk_fma_f32 v[34:35], v[108:109], v[38:39], v[34:35]
	s_waitcnt vmcnt(19)
	v_lshlrev_b32_e32 v40, 16, v169
	v_and_b32_e32 v41, 0xffff0000, v169
	v_pk_fma_f32 v[34:35], v[110:111], v[40:41], v[34:35]
	s_or_b32 s40, s93, 2
	v_cvt_pk_bf16_f32 v42, v34, v35
	v_pk_fma_f32 v[34:35], v[104:105], v[36:37], v[100:101]
	s_waitcnt vmcnt(18)
	v_lshlrev_b32_e32 v36, 16, v170
	v_pk_fma_f32 v[34:35], v[106:107], v[38:39], v[34:35]
	v_and_b32_e32 v37, 0xffff0000, v170
	v_pk_fma_f32 v[34:35], v[108:109], v[40:41], v[34:35]
	s_cmpk_gt_u32 s40, 0x7d
	v_pk_fma_f32 v[34:35], v[110:111], v[36:37], v[34:35]
	s_nop 0
	v_cvt_pk_bf16_f32 v34, v34, v35
	ds_write2_b32 v183, v42, v34 offset1:72
	v_pk_fma_f32 v[34:35], v[104:105], v[38:39], v[100:101]
	s_waitcnt vmcnt(17)
	v_lshlrev_b32_e32 v38, 16, v171
	v_pk_fma_f32 v[34:35], v[106:107], v[40:41], v[34:35]
	v_and_b32_e32 v39, 0xffff0000, v171
	v_pk_fma_f32 v[34:35], v[108:109], v[36:37], v[34:35]
	s_nop 0
	v_pk_fma_f32 v[34:35], v[110:111], v[38:39], v[34:35]
	s_nop 0
	v_cvt_pk_bf16_f32 v42, v34, v35
	v_pk_fma_f32 v[34:35], v[104:105], v[40:41], v[100:101]
	s_waitcnt vmcnt(16)
	v_lshlrev_b32_e32 v40, 16, v172
	v_pk_fma_f32 v[34:35], v[106:107], v[36:37], v[34:35]
	v_and_b32_e32 v41, 0xffff0000, v172
	v_pk_fma_f32 v[34:35], v[108:109], v[38:39], v[34:35]
	s_nop 0
	v_pk_fma_f32 v[34:35], v[110:111], v[40:41], v[34:35]
	s_nop 0
	v_cvt_pk_bf16_f32 v34, v34, v35
	ds_write2_b32 v183, v42, v34 offset0:144 offset1:216
	v_pk_fma_f32 v[34:35], v[104:105], v[36:37], v[100:101]
	s_waitcnt vmcnt(15)
	v_lshlrev_b32_e32 v36, 16, v173
	v_pk_fma_f32 v[34:35], v[106:107], v[38:39], v[34:35]
	v_and_b32_e32 v37, 0xffff0000, v173
	v_pk_fma_f32 v[34:35], v[108:109], v[40:41], v[34:35]
	s_nop 0
	v_pk_fma_f32 v[34:35], v[110:111], v[36:37], v[34:35]
	s_nop 0
	v_cvt_pk_bf16_f32 v42, v34, v35
	v_pk_fma_f32 v[34:35], v[104:105], v[38:39], v[100:101]
	s_waitcnt vmcnt(14)
	v_lshlrev_b32_e32 v38, 16, v174
	v_pk_fma_f32 v[34:35], v[106:107], v[40:41], v[34:35]
	v_and_b32_e32 v39, 0xffff0000, v174
	v_pk_fma_f32 v[34:35], v[108:109], v[36:37], v[34:35]
	s_nop 0
	v_pk_fma_f32 v[34:35], v[110:111], v[38:39], v[34:35]
	s_nop 0
	v_cvt_pk_bf16_f32 v34, v34, v35
	ds_write2_b32 v182, v42, v34 offset0:32 offset1:104
	v_pk_fma_f32 v[34:35], v[104:105], v[40:41], v[100:101]
	s_waitcnt vmcnt(13)
	v_lshlrev_b32_e32 v40, 16, v175
	v_pk_fma_f32 v[34:35], v[106:107], v[36:37], v[34:35]
	v_and_b32_e32 v41, 0xffff0000, v175
	v_pk_fma_f32 v[34:35], v[108:109], v[38:39], v[34:35]
	s_nop 0
	v_pk_fma_f32 v[34:35], v[110:111], v[40:41], v[34:35]
	s_nop 0
	v_cvt_pk_bf16_f32 v42, v34, v35
	v_pk_fma_f32 v[34:35], v[104:105], v[36:37], v[100:101]
	s_waitcnt vmcnt(12)
	v_lshlrev_b32_e32 v36, 16, v176
	v_pk_fma_f32 v[34:35], v[106:107], v[38:39], v[34:35]
	v_and_b32_e32 v37, 0xffff0000, v176
	v_pk_fma_f32 v[34:35], v[108:109], v[40:41], v[34:35]
	s_nop 0
	v_pk_fma_f32 v[34:35], v[110:111], v[36:37], v[34:35]
	s_nop 0
	v_cvt_pk_bf16_f32 v34, v34, v35
	ds_write2_b32 v182, v42, v34 offset0:176 offset1:248
	s_cbranch_scc1 .LBB0_281
	s_nop 0
	s_nop 0
	s_nop 0
	v_readfirstlane_b32 s98, v50
	v_readfirstlane_b32 s99, v51
	s_add_u32 s100, s98, 0x25ee4000
	s_addc_u32 s101, s99, 0x0
	global_load_dword v130, v208, s[100:101]
	s_nop 0
	s_nop 0
	s_add_u32 s100, s98, 0x25ef0000
	s_addc_u32 s101, s99, 0x0
	global_load_dword v132, v208, s[100:101]
	s_nop 0
	s_nop 0
	s_add_u32 s100, s98, 0x25efc000
	s_addc_u32 s101, s99, 0x0
	global_load_dword v134, v208, s[100:101]
	s_nop 0
	s_nop 0
	s_add_u32 s100, s98, 0x25f08000
	s_addc_u32 s101, s99, 0x0
	global_load_dword v169, v208, s[100:101]
	s_nop 0
	s_nop 0
	s_add_u32 s100, s98, 0x25f14000
	s_addc_u32 s101, s99, 0x0
	global_load_dword v170, v208, s[100:101]
	s_nop 0
	s_nop 0
	s_add_u32 s100, s98, 0x25f20000
	s_addc_u32 s101, s99, 0x0
	global_load_dword v171, v208, s[100:101]
	s_nop 0
	s_nop 0
	s_add_u32 s100, s98, 0x25f2c000
	s_addc_u32 s101, s99, 0x0
	global_load_dword v172, v208, s[100:101]
	s_nop 0
	s_nop 0
	s_add_u32 s100, s98, 0x25f38000
	s_addc_u32 s101, s99, 0x0
	global_load_dword v173, v208, s[100:101]
	s_nop 0
	s_nop 0
	s_add_u32 s100, s98, 0x25f44000
	s_addc_u32 s101, s99, 0x0
	global_load_dword v174, v208, s[100:101]
	s_nop 0
	s_nop 0
	s_add_u32 s100, s98, 0x25f50000
	s_addc_u32 s101, s99, 0x0
	global_load_dword v175, v208, s[100:101]
	s_nop 0
	s_nop 0
	s_add_u32 s100, s98, 0x25f5c000
	s_addc_u32 s101, s99, 0x0
	global_load_dword v176, v208, s[100:101]
.LBB0_281:
	s_nop 0
	s_nop 0
	s_nop 0
	v_readfirstlane_b32 s98, v52
	v_readfirstlane_b32 s99, v53
	s_add_u32 s100, s98, 0x25c0a000
	s_addc_u32 s101, s99, 0x0
	global_load_ushort v59, v209, s[100:101]
	s_nop 0
	s_nop 0
	s_add_u32 s100, s98, 0x25c16000
	s_addc_u32 s101, s99, 0x0
	global_load_ushort v60, v209, s[100:101]
	s_nop 0
	s_nop 0
	s_add_u32 s100, s98, 0x25c22000
	s_addc_u32 s101, s99, 0x0
	global_load_ushort v61, v209, s[100:101]
	s_nop 0
	s_nop 0
	s_add_u32 s100, s98, 0x25c2e000
	s_addc_u32 s101, s99, 0x0
	global_load_ushort v62, v209, s[100:101]
	s_and_b64 vcc, exec, s[36:37]
	s_cbranch_vccnz .LBB0_284
	s_cmpk_gt_u32 s87, 0x687f
	s_cbranch_scc0 .LBB0_285
	s_add_i32 s84, s87, 0xffff9780
	s_mov_b64 s[40:41], s[52:53]
	s_movk_i32 s78, 0x1000
	s_cbranch_execz .LBB0_286
	s_branch .LBB0_287

; DI void rglru_scan_unit(Frame& F, const Mix0Args& a, int u) {
;     ...
;         for (int i = 0; i < 4; ++i) gb_cur[i] = gbr[i];
.LBB0_291:
	s_cmpk_gt_u32 s78, 0x7d
	s_cbranch_scc1 .LBB0_293
	s_nop 0
	s_nop 0
	s_nop 0
	v_readfirstlane_b32 s98, v50
	v_readfirstlane_b32 s99, v51
	s_add_u32 s100, s98, 0x261e4000
	s_addc_u32 s101, s99, 0x0
	global_load_dword v130, v208, s[100:101]
	s_nop 0
	s_nop 0
	s_add_u32 s100, s98, 0x261f0000
	s_addc_u32 s101, s99, 0x0
	global_load_dword v132, v208, s[100:101]
	s_nop 0
	s_nop 0
	s_add_u32 s100, s98, 0x261fc000
	s_addc_u32 s101, s99, 0x0
	global_load_dword v134, v208, s[100:101]
	s_nop 0
	s_nop 0
	s_add_u32 s100, s98, 0x26208000
	s_addc_u32 s101, s99, 0x0
	global_load_dword v169, v208, s[100:101]
	s_nop 0
	s_nop 0
	s_add_u32 s100, s98, 0x26214000
	s_addc_u32 s101, s99, 0x0
	global_load_dword v170, v208, s[100:101]
	s_nop 0
	s_nop 0
	s_add_u32 s100, s98, 0x26220000
	s_addc_u32 s101, s99, 0x0
	global_load_dword v171, v208, s[100:101]
	s_nop 0
	s_nop 0
	s_add_u32 s100, s98, 0x2622c000
	s_addc_u32 s101, s99, 0x0
	global_load_dword v172, v208, s[100:101]
	s_nop 0
	s_nop 0
	s_add_u32 s100, s98, 0x26238000
	s_addc_u32 s101, s99, 0x0
	global_load_dword v173, v208, s[100:101]
	s_nop 0
	s_nop 0
	s_add_u32 s100, s98, 0x26244000
	s_addc_u32 s101, s99, 0x0
	global_load_dword v174, v208, s[100:101]
	s_nop 0
	s_nop 0
	s_nop 0
	s_nop 0
	s_add_u32 s100, s98, 0x26250000
	s_addc_u32 s101, s99, 0x0
	global_load_dword v175, v208, s[100:101]
	s_add_u32 s100, s98, 0x2625c000
	s_addc_u32 s101, s99, 0x0
	global_load_dword v176, v208, s[100:101]
.LBB0_293:
	s_waitcnt vmcnt(11)
	v_and_b32_e32 v71, 0xffff, v59
	s_waitcnt vmcnt(10)
	v_and_b32_e32 v70, 0xffff, v60
	s_waitcnt vmcnt(9)
	v_and_b32_e32 v69, 0xffff, v61
	s_waitcnt vmcnt(8)
	v_and_b32_e32 v68, 0xffff, v62
	s_andn2_b64 vcc, exec, s[40:41]
	v_mov_b32_e32 v178, v68
	v_mov_b32_e32 v179, v69
	v_mov_b32_e32 v180, v70
	v_mov_b32_e32 v181, v71
	s_cbranch_vccnz .LBB0_295
	s_nop 0
	s_nop 0
	s_nop 0
	v_readfirstlane_b32 s98, v52
	v_readfirstlane_b32 s99, v53
	s_add_u32 s100, s98, 0x25f0a000
	s_addc_u32 s101, s99, 0x0
	global_load_ushort v181, v209, s[100:101]
	s_nop 0
	s_nop 0
	s_add_u32 s100, s98, 0x25f16000
	s_addc_u32 s101, s99, 0x0
	global_load_ushort v180, v209, s[100:101]
	s_nop 0
	s_nop 0
	s_add_u32 s100, s98, 0x25f22000
	s_addc_u32 s101, s99, 0x0
	global_load_ushort v179, v209, s[100:101]
	s_nop 0
	s_nop 0
	s_add_u32 s100, s98, 0x25f2e000
	s_addc_u32 s101, s99, 0x0
	global_load_ushort v178, v209, s[100:101]

; DI void rglru_scan_unit(Frame& F, const Mix0Args& a, int u) {
;     ...
;     const size_t rowbase = (size_t)b * SEQ;
;     const bf16* xcol = a.proj + C_XB + cb + 2 * c2;
;     const bf16* gbcol = a.proj + C_GB + co; bf16* obcol = a.outp + a.ob_col + co;
;     ...
;     for (; n < NCH; ++n) rg_step(n, CvQ<-1>{});
.LBB0_319:
	s_cmpk_gt_u32 s93, 0x7f
	s_cbranch_scc1 .LBB0_330
	v_readlane_b32 s3, v253, 50
	s_lshl_b32 s40, s3, 6
	v_mad_i64_i32 v[4:5], s[2:3], s2, v163, v[114:115]
	v_readlane_b32 s2, v252, 8
	v_readlane_b32 s8, v253, 57
	v_readlane_b32 s3, v252, 9
	v_mov_b32_e32 v113, v83
	v_readlane_b32 s9, v253, 58
	v_lshl_add_u32 v82, s93, 6, v154
	s_or_b64 s[2:3], s[80:81], s[2:3]
	v_lshl_add_u64 v[2:3], s[8:9], 0, v[112:113]
	s_mul_hi_u32 s9, s93, 0x300000
	s_mul_i32 s8, s93, 0x300000
	v_lshl_add_u64 v[4:5], v[96:97], 0, v[4:5]
	v_lshl_add_u64 v[6:7], v[98:99], 0, s[2:3]
	s_nop 0
	v_readfirstlane_b32 s98, v6
	v_readfirstlane_b32 s99, v4
	s_nop 1
	v_subrev_u32_e32 v208, s98, v6
	v_subrev_u32_e32 v209, s99, v4
	s_mov_b64 s[2:3], 0x17d00000
	v_mov_b64_e32 v[8:9], v[82:83]
	s_branch .LBB0_322

; #define RG_LOAD(n_) do { const long r0_ = (long)rowbase + (long)(n_) * 64; \
;         _Pragma("unroll") for (int i = 0; i < 11; ++i) xr[i] = ((n_) == 0 && 8 * rg - 3 + i < 0) ? 0u : *(const unsigned*)(xcol + (size_t)(r0_ + 8 * rg - 3 + i) * N1); } while (0)
; #define RG_LOADG(n_) do { const long r0_ = (long)rowbase + (long)(n_) * 64; \
;         _Pragma("unroll") for (int i = 0; i < 4; ++i) gbr[i] = *(const unsigned short*)(gbcol + (size_t)(r0_ + l0_ + 4 * fq + i) * N1); } while (0)
; #define RG_STAGE(xc_) do { LAS uchar* X_ = (xc_); \
;         _Pragma("unroll") for (int i = 0; i < 8; ++i) { f32x2 s2 = (f32x2){cbs[0], cbs[1]}; \
;             _Pragma("unroll") for (int k = 0; k < 4; ++k) s2 += (f32x2){cw[k][0], cw[k][1]} * (f32x2){bflo(xr[i + k]), bfhi(xr[i + k])}; \
;             *(LAS unsigned*)(X_ + (8 * rg + i) * S128 + c2 * 4) = pk2(s2.x, s2.y); } } while (0)
; DI void rglru_scan_unit(Frame& F, const Mix0Args& a, int u) {
;     ...
;         for (int i = 0; i < 4; ++i) gb_cur[i] = gbr[i];
;         if (n + 1 < NCH) RG_STAGE(XCn);
;         if constexpr (CQ == 0) { if (n > 0) { const int ip = ((n >> 2) - 1) * NGW + gw; if (ip < CV_NIT) cv_finish(a.cv, ip, lane, cq0, cq1, cq2, cq3, CVS); } }
;         if (n + 2 < NCH) RG_LOAD(n + 2);
;         if (n + 1 < NCH) RG_LOADG(n + 1);
.LBB0_324:
	s_cmpk_gt_u32 s93, 0x7d
	s_cbranch_scc1 .LBB0_326
	v_lshl_add_u64 v[10:11], v[6:7], 0, s[8:9]
	s_nop 0
	s_nop 0
	s_nop 0
	v_readfirstlane_b32 s98, v10
	v_readfirstlane_b32 s99, v11
	s_add_u32 s100, s98, 0x258e4000
	s_addc_u32 s101, s99, 0x0
	global_load_dword v130, v208, s[100:101]
	s_nop 0
	s_nop 0
	s_add_u32 s100, s98, 0x258f0000
	s_addc_u32 s101, s99, 0x0
	global_load_dword v132, v208, s[100:101]
	s_nop 0
	s_nop 0
	s_add_u32 s100, s98, 0x258fc000
	s_addc_u32 s101, s99, 0x0
	global_load_dword v134, v208, s[100:101]
	s_nop 0
	s_nop 0
	s_add_u32 s100, s98, 0x25908000
	s_addc_u32 s101, s99, 0x0
	global_load_dword v169, v208, s[100:101]
	s_nop 0
	s_nop 0
	s_add_u32 s100, s98, 0x25914000
	s_addc_u32 s101, s99, 0x0
	global_load_dword v170, v208, s[100:101]
	s_nop 0
	s_nop 0
	s_add_u32 s100, s98, 0x25920000
	s_addc_u32 s101, s99, 0x0
	global_load_dword v171, v208, s[100:101]
	s_nop 0
	s_nop 0
	s_add_u32 s100, s98, 0x2592c000
	s_addc_u32 s101, s99, 0x0
	global_load_dword v172, v208, s[100:101]
	s_nop 0
	s_nop 0
	s_add_u32 s100, s98, 0x25938000
	s_addc_u32 s101, s99, 0x0
	global_load_dword v173, v208, s[100:101]
	s_nop 0
	s_nop 0
	s_add_u32 s100, s98, 0x25944000
	s_addc_u32 s101, s99, 0x0
	global_load_dword v174, v208, s[100:101]
	s_nop 0
	s_nop 0
	s_nop 0
	s_nop 0
	s_add_u32 s100, s98, 0x25950000
	s_addc_u32 s101, s99, 0x0
	global_load_dword v175, v208, s[100:101]
	s_add_u32 s100, s98, 0x2595c000
	s_addc_u32 s101, s99, 0x0
	global_load_dword v176, v208, s[100:101]
.LBB0_326:
	s_andn2_b64 vcc, exec, s[36:37]
	s_waitcnt vmcnt(8)
	v_mov_b32_e32 v13, v178
	v_mov_b32_e32 v12, v179
	v_mov_b32_e32 v11, v180
	v_mov_b32_e32 v10, v181
	s_cbranch_vccnz .LBB0_328
	v_lshl_add_u64 v[14:15], v[4:5], 0, s[8:9]
	s_nop 0
	s_nop 0
	s_nop 0
	s_nop 0
	s_nop 0
	v_readfirstlane_b32 s98, v14
	v_readfirstlane_b32 s99, v15
	s_add_u32 s100, s98, 0x2560a000
	s_addc_u32 s101, s99, 0x0
	global_load_ushort v10, v209, s[100:101]
	s_add_u32 s100, s98, 0x25616000
	s_addc_u32 s101, s99, 0x0
	global_load_ushort v11, v209, s[100:101]
	s_nop 0
	s_nop 0
	s_nop 0
	s_nop 0
	s_add_u32 s100, s98, 0x25622000
	s_addc_u32 s101, s99, 0x0
	global_load_ushort v12, v209, s[100:101]
	s_add_u32 s100, s98, 0x2562e000
	s_addc_u32 s101, s99, 0x0
	global_load_ushort v13, v209, s[100:101]
